# v13 + attention queue pop issued by wave 0 right before its 8 output stores, waited with vmcnt(8) at the item head
# speedup vs baseline: 1.0040x; 1.0012x over previous
; #define LAS __attribute__((address_space(3)))
; __device__ __forceinline__ int swap23(int r) { return (r & ~12) | ((r & 4) << 1) | ((r & 8) >> 1); }
; __device__ __forceinline__ void phase_attn(const Params& p, LAS unsigned char* lds, unsigned* queue) {
;     const int tid = threadIdx.x, lane = tid & 63, w = __builtin_amdgcn_readfirstlane(tid >> 6), r = lane & 31, hh = lane >> 5;
;     const bf16_t* Qg = (const bf16_t*)(p.ws + WS_Q); const bf16_t* Kg = (const bf16_t*)(p.ws + WS_K); const bf16_t* VTg = (const bf16_t*)(p.ws + WS_VT);
;     const bf16_t* SZA = (const bf16_t*)(p.ws + WS_SZA); const float* KSUM = (const float*)(p.ws + WS_KSUM);
;     bf16_t* MIXED = (bf16_t*)(p.ws + WS_XB);
;     constexpr int ROWB = 144, TILEB = 64 * ROWB, BUFB = 2 * TILEB;
;     const int srow = tid >> 3, sch = tid & 7;
;     const unsigned st_off = (unsigned)(srow * ROWB + sch * 16);
;     const unsigned kf_off = (unsigned)(swap23(r) * ROWB + hh * 16);
;     const unsigned vf_off = (unsigned)(TILEB + r * ROWB + hh * 16);
;     volatile LAS unsigned* tick = (volatile LAS unsigned*)(lds + LDS_CTL + 8);
;     for (;;) {
;         if (tid == 0) *tick = __hip_atomic_fetch_add(queue, 1u, __ATOMIC_RELAXED, __HIP_MEMORY_SCOPE_AGENT);
.LBB0_330:
	s_add_u32 s0, s78, 0xbd03a00
	s_addc_u32 s1, s79, 0
	v_and_b32_e32 v3, 7, v0
	v_lshlrev_b32_e32 v5, 1, v0
	v_writelane_b32 v255, s0, 6
	v_bfe_u32 v8, v0, 5, 1
	v_lshlrev_b32_e32 v4, 4, v3
	v_and_b32_e32 v3, 19, v0
	v_and_b32_e32 v5, 8, v5
	v_and_b32_e32 v2, 4, v2
	v_writelane_b32 v255, s1, 7
	s_movk_i32 s1, 0x90
	v_or3_b32 v3, v3, v5, v2
	v_lshlrev_b32_e32 v2, 4, v8
	v_mad_u32_u24 v197, v3, s1, v2
	v_mov_b32_e32 v3, 0
	v_readfirstlane_b32 s0, v0
	v_lshlrev_b32_e32 v6, 5, v8
	v_mov_b32_e32 v7, v3
	s_lshr_b32 s3, s0, 1
	v_lshl_add_u64 v[180:181], s[10:11], 0, v[6:7]
	v_lshlrev_b32_e32 v6, 12, v200
	s_and_b32 s3, s3, 0x7fffffe0
	v_mov_b32_e32 v5, v3
	v_lshl_add_u64 v[6:7], s[8:9], 0, v[6:7]
	v_mbcnt_hi_u32_b32 v192, -1, v250
	v_mul_u32_u24_e32 v9, 0x90, v200
	v_or_b32_e32 v199, s3, v212
	v_lshl_add_u64 v[178:179], s[12:13], 0, v[2:3]
	v_lshl_add_u64 v[184:185], v[6:7], 0, v[4:5]
	s_lshr_b32 s3, s0, 7
	v_lshlrev_b32_e32 v6, 2, v8
	v_mad_u32_u24 v205, v212, s1, v2
	s_add_i32 s90, 0, 0x22008
	v_and_b32_e32 v2, 64, v192
	v_lshlrev_b32_e32 v203, 3, v8
	v_lshl_add_u64 v[182:183], s[6:7], 0, v[4:5]
	s_mov_b32 s83, 0
	v_add3_u32 v204, v9, v4, 0
	s_lshl_b32 s88, s3, 6
	s_add_i32 s89, s3, -1
	v_mov_b32_e32 v212, s90
	s_mov_b32 s91, 0x41000000
	v_lshlrev_b32_e32 v186, 1, v6
	v_xor_b32_e32 v193, 32, v192
	v_add_u32_e32 v202, 64, v2
	v_mov_b32_e32 v211, 0xf149f2ca
	s_and_saveexec_b64 s[100:101], s[92:93]
	s_cbranch_execz .Lpop0_done
	v_mov_b32_e32 v217, 1
	v_mov_b32_e32 v251, 0
	v_readlane_b32 s98, v255, 6
	v_readlane_b32 s99, v255, 7
	s_nop 4
	global_atomic_add v217, v251, v217, s[98:99] sc0
	s_waitcnt vmcnt(0)

; __device__ __forceinline__ unsigned pk2(float lo, float hi) { const f32x2c_t v = {lo, hi}; return __builtin_bit_cast(unsigned, __builtin_convertvector(v, bf16x2c_t)); }
; __device__ __forceinline__ float bflo(unsigned w) { return __uint_as_float(w << 16); }
; __device__ __forceinline__ float bfhi(unsigned w) { return __uint_as_float(w & 0xffff0000u); }
; __device__ __forceinline__ void phase_attn(const Params& p, LAS unsigned char* lds, unsigned* queue) {
;     ...
;         if (tid == 0) *tick = __hip_atomic_fetch_add(queue, 1u, __ATOMIC_RELAXED, __HIP_MEMORY_SCOPE_AGENT);
;     ...
;         lrun += __shfl_xor(lrun, 32);
;         const float inv = 1.f / lrun;
;         const size_t row = (size_t)b * 2048 + qpos;
; #pragma unroll
;         for (int dt = 0; dt < 2; ++dt)
; #pragma unroll
;             for (int g4 = 0; g4 < 4; ++g4) {
;                 const int d0 = 32 * dt + 8 * g4 + 4 * hh;
;                 const u32x2 z2 = *(const u32x2*)(SZA + row * 512 + h * 64 + d0);
;                 float o0, o1, o2, o3;
;                 if (dt == 0) { o0 = O0[4 * g4]; o1 = O0[4 * g4 + 1]; o2 = O0[4 * g4 + 2]; o3 = O0[4 * g4 + 3]; }
;                 else { o0 = O1[4 * g4]; o1 = O1[4 * g4 + 1]; o2 = O1[4 * g4 + 2]; o3 = O1[4 * g4 + 3]; }
;                 o0 *= inv * bflo(z2[0]); o1 *= inv * bfhi(z2[0]); o2 *= inv * bflo(z2[1]); o3 *= inv * bfhi(z2[1]);
;                 *(u32x2*)(MIXED + row * 1024 + h * 64 + d0) = (u32x2){pk2(o0, o1), pk2(o2, o3)};
;             }
;     }
.LBB0_331:
	s_waitcnt vmcnt(0)
	s_lshl_b32 s0, s97, 8
	s_and_b32 s0, s0, 0x3800
	v_add_u32_e32 v2, s0, v187
	v_readlane_b32 s0, v255, 4
	v_lshlrev_b64 v[6:7], 10, v[2:3]
	v_readlane_b32 s1, v255, 5
	v_mov_b32_e32 v187, v3
	v_cmp_lt_i32_e32 vcc, v193, v202
	v_lshl_add_u64 v[6:7], s[0:1], 0, v[6:7]
	s_lshl_b32 s0, s96, 7
	s_and_b32 s82, s0, 0x380
	v_lshl_add_u64 v[6:7], v[6:7], 0, s[82:83]
	v_lshl_add_u64 v[6:7], v[6:7], 0, v[186:187]
	v_mov_b64_e32 v[8:9], v[218:219]
	v_mov_b64_e32 v[10:11], v[220:221]
	v_mov_b64_e32 v[12:13], v[222:223]
	v_mov_b64_e32 v[14:15], v[224:225]
	v_mov_b64_e32 v[16:17], v[226:227]
	v_mov_b64_e32 v[18:19], v[228:229]
	v_cndmask_b32_e32 v4, v192, v193, vcc
	v_lshlrev_b32_e32 v4, 2, v4
	ds_bpermute_b32 v4, v4, v5
	v_lshlrev_b64 v[20:21], 11, v[2:3]
	v_readlane_b32 s78, v255, 0
	v_readlane_b32 s79, v255, 1
	s_mov_b64 s[4:5], 0
	s_waitcnt lgkmcnt(0)
	v_add_f32_e32 v2, v5, v4
	v_mov_b64_e32 v[4:5], v[230:231]
	v_div_scale_f32 v22, s[0:1], v2, v2, 1.0
	v_mov_b64_e32 v[6:7], v[232:233]
	v_rcp_f32_e32 v23, v22
	v_div_scale_f32 v24, vcc, 1.0, v2, 1.0
	v_lshl_add_u64 v[20:21], s[78:79], 0, v[20:21]
	v_fma_f32 v25, -v22, v23, 1.0
	v_fmac_f32_e32 v23, v25, v23
	v_mul_f32_e32 v25, v24, v23
	v_fma_f32 v26, -v22, v25, v24
	v_fmac_f32_e32 v25, v26, v23
	v_fma_f32 v22, -v22, v25, v24
	v_div_fmas_f32 v22, v22, v23, v25
	v_div_fixup_f32 v2, v22, v2, 1.0
	v_lshl_add_u64 v[20:21], v[20:21], 0, s[82:83]
	v_lshl_add_u64 v[20:21], v[20:21], 0, v[186:187]
	v_lshlrev_b32_e32 v22, 16, v8
	v_and_b32_e32 v23, 0xffff0000, v8
	v_lshlrev_b32_e32 v8, 16, v9
	v_and_b32_e32 v9, 0xffff0000, v9
	v_lshlrev_b32_e32 v24, 16, v10
	v_and_b32_e32 v25, 0xffff0000, v10
	v_lshlrev_b32_e32 v10, 16, v11
	v_and_b32_e32 v11, 0xffff0000, v11
	v_lshlrev_b32_e32 v26, 16, v12
	v_and_b32_e32 v27, 0xffff0000, v12
	v_lshlrev_b32_e32 v12, 16, v13
	v_and_b32_e32 v13, 0xffff0000, v13
	v_lshlrev_b32_e32 v28, 16, v14
	v_and_b32_e32 v29, 0xffff0000, v14
	v_lshlrev_b32_e32 v14, 16, v15
	v_and_b32_e32 v15, 0xffff0000, v15
	v_pk_mul_f32 v[22:23], v[2:3], v[22:23] op_sel_hi:[0,1]
	v_pk_mul_f32 v[8:9], v[2:3], v[8:9] op_sel_hi:[0,1]
	v_pk_mul_f32 v[24:25], v[2:3], v[24:25] op_sel_hi:[0,1]
	v_pk_mul_f32 v[10:11], v[2:3], v[10:11] op_sel_hi:[0,1]
	v_lshlrev_b32_e32 v30, 16, v16
	v_and_b32_e32 v31, 0xffff0000, v16
	v_lshlrev_b32_e32 v16, 16, v17
	v_and_b32_e32 v17, 0xffff0000, v17
	v_pk_mul_f32 v[26:27], v[2:3], v[26:27] op_sel_hi:[0,1]
	v_pk_mul_f32 v[12:13], v[2:3], v[12:13] op_sel_hi:[0,1]
	v_pk_mul_f32 v[28:29], v[2:3], v[28:29] op_sel_hi:[0,1]
	v_pk_mul_f32 v[14:15], v[2:3], v[14:15] op_sel_hi:[0,1]
	v_pk_mul_f32 v[22:23], v[98:99], v[22:23]
	v_pk_mul_f32 v[8:9], v[100:101], v[8:9]
	v_pk_mul_f32 v[24:25], v[102:103], v[24:25]
	v_pk_mul_f32 v[10:11], v[104:105], v[10:11]
	v_pk_mul_f32 v[30:31], v[2:3], v[30:31] op_sel_hi:[0,1]
	v_pk_mul_f32 v[16:17], v[2:3], v[16:17] op_sel_hi:[0,1]
	v_pk_mul_f32 v[26:27], v[106:107], v[26:27]
	v_pk_mul_f32 v[12:13], v[108:109], v[12:13]
	v_pk_mul_f32 v[28:29], v[110:111], v[28:29]
	v_pk_mul_f32 v[14:15], v[112:113], v[14:15]
	v_cvt_pk_bf16_f32 v22, v22, v23
	v_cvt_pk_bf16_f32 v23, v8, v9
	v_cvt_pk_bf16_f32 v8, v24, v25
	v_cvt_pk_bf16_f32 v9, v10, v11
	v_pk_mul_f32 v[30:31], v[82:83], v[30:31]
	v_cvt_pk_bf16_f32 v10, v26, v27
	v_cvt_pk_bf16_f32 v11, v12, v13
	v_cvt_pk_bf16_f32 v12, v28, v29
	v_cvt_pk_bf16_f32 v13, v14, v15
	s_and_saveexec_b64 s[100:101], s[92:93]
	s_cbranch_execz .Lpop_ep_done
	v_mov_b32_e32 v217, 1
	v_mov_b32_e32 v251, 0
	v_readlane_b32 s98, v255, 6
	v_readlane_b32 s99, v255, 7
	s_nop 4
	global_atomic_add v217, v251, v217, s[98:99] sc0
.Lpop_ep_done:
	s_or_b64 exec, exec, s[100:101]
	global_store_dwordx2 v[20:21], v[22:23], off
	global_store_dwordx2 v[20:21], v[8:9], off offset:16
	global_store_dwordx2 v[20:21], v[10:11], off offset:32
	global_store_dwordx2 v[20:21], v[12:13], off offset:48
	v_pk_mul_f32 v[8:9], v[84:85], v[16:17]
	v_cvt_pk_bf16_f32 v10, v30, v31
	v_cvt_pk_bf16_f32 v11, v8, v9
	global_store_dwordx2 v[20:21], v[10:11], off offset:64
	v_lshlrev_b32_e32 v8, 16, v18
	v_and_b32_e32 v9, 0xffff0000, v18
	v_lshlrev_b32_e32 v10, 16, v19
	v_and_b32_e32 v11, 0xffff0000, v19
	v_pk_mul_f32 v[8:9], v[2:3], v[8:9] op_sel_hi:[0,1]
	v_pk_mul_f32 v[10:11], v[2:3], v[10:11] op_sel_hi:[0,1]
	v_pk_mul_f32 v[8:9], v[86:87], v[8:9]
	v_pk_mul_f32 v[10:11], v[88:89], v[10:11]
	v_cvt_pk_bf16_f32 v8, v8, v9
	v_cvt_pk_bf16_f32 v9, v10, v11
	global_store_dwordx2 v[20:21], v[8:9], off offset:80
	v_lshlrev_b32_e32 v8, 16, v4
	v_and_b32_e32 v9, 0xffff0000, v4
	v_lshlrev_b32_e32 v4, 16, v5
	v_and_b32_e32 v5, 0xffff0000, v5
	v_pk_mul_f32 v[8:9], v[2:3], v[8:9] op_sel_hi:[0,1]
	v_pk_mul_f32 v[4:5], v[2:3], v[4:5] op_sel_hi:[0,1]
	v_pk_mul_f32 v[8:9], v[90:91], v[8:9]
	v_pk_mul_f32 v[4:5], v[92:93], v[4:5]
	v_cvt_pk_bf16_f32 v8, v8, v9
	v_cvt_pk_bf16_f32 v9, v4, v5
	v_lshlrev_b32_e32 v4, 16, v6
	v_and_b32_e32 v5, 0xffff0000, v6
	v_lshlrev_b32_e32 v6, 16, v7
	v_and_b32_e32 v7, 0xffff0000, v7
	v_pk_mul_f32 v[4:5], v[2:3], v[4:5] op_sel_hi:[0,1]
	v_pk_mul_f32 v[6:7], v[2:3], v[6:7] op_sel_hi:[0,1]
	v_pk_mul_f32 v[4:5], v[94:95], v[4:5]
	v_pk_mul_f32 v[6:7], v[96:97], v[6:7]
	v_cvt_pk_bf16_f32 v4, v4, v5
	v_cvt_pk_bf16_f32 v5, v6, v7
	global_store_dwordx2 v[20:21], v[8:9], off offset:96
	global_store_dwordx2 v[20:21], v[4:5], off offset:112
